# attention fast trip: next-tile K fragment reads one gap earlier (gaps 2-5) on top of the one-gap-early step barrier
# speedup vs baseline: 1.0127x; 1.0002x over previous
.Lf3_0_486:
	s_waitcnt lgkmcnt(14)
	v_mfma_f32_32x32x16_bf16 v[18:33], v[138:141], v[178:181], v[18:33]
	v_exp_f32_e32 v98, v98
	v_exp_f32_e32 v99, v99
	v_exp_f32_e32 v100, v100
	v_exp_f32_e32 v101, v101
	ds_read_b128 v[62:65], v202 offset:16384
	ds_read_b128 v[178:181], v202 offset:18432
	s_waitcnt lgkmcnt(14)
	v_mfma_f32_32x32x16_bf16 v[2:17], v[138:141], v[174:177], v[2:17]
	v_exp_f32_e32 v102, v102
	v_exp_f32_e32 v103, v103
	v_exp_f32_e32 v104, v104
	v_exp_f32_e32 v105, v105
	ds_read_b128 v[174:177], v202 offset:16896
	ds_read_b128 v[170:173], v202 offset:18944
	s_waitcnt lgkmcnt(14)
	v_mfma_f32_32x32x16_bf16 v[18:33], v[130:133], v[66:69], v[18:33]
	v_exp_f32_e32 v106, v106
	v_exp_f32_e32 v107, v107
	v_exp_f32_e32 v108, v108
	v_exp_f32_e32 v109, v109
	ds_read_b128 v[166:169], v202 offset:20480
	ds_read_b128 v[162:165], v202 offset:20992
	s_waitcnt lgkmcnt(14)
	v_mfma_f32_32x32x16_bf16 v[2:17], v[130:133], v[70:73], v[2:17]
	v_exp_f32_e32 v110, v110
	v_exp_f32_e32 v111, v111
	v_exp_f32_e32 v112, v112
	v_exp_f32_e32 v113, v113
	ds_read_b128 v[158:161], v202 offset:22528
	ds_read_b128 v[154:157], v202 offset:23040
	s_waitcnt lgkmcnt(14)
	v_mfma_f32_32x32x16_bf16 v[18:33], v[122:125], v[74:77], v[18:33]
	v_exp_f32_e32 v82, v82
	v_exp_f32_e32 v83, v83
	v_exp_f32_e32 v84, v84
	v_exp_f32_e32 v85, v85
	s_waitcnt lgkmcnt(12)
	v_mfma_f32_32x32x16_bf16 v[2:17], v[122:125], v[50:53], v[2:17]
	v_exp_f32_e32 v86, v86
	v_exp_f32_e32 v87, v87
	v_exp_f32_e32 v88, v88
	v_exp_f32_e32 v89, v89
	s_waitcnt lgkmcnt(10)
	v_mfma_f32_32x32x16_bf16 v[18:33], v[114:117], v[54:57], v[18:33]
	v_exp_f32_e32 v90, v90
	v_exp_f32_e32 v91, v91
	v_exp_f32_e32 v92, v92
	v_exp_f32_e32 v93, v93
	s_waitcnt vmcnt(2) lgkmcnt(0)
	s_barrier
	s_waitcnt lgkmcnt(8)
	v_mfma_f32_32x32x16_bf16 v[2:17], v[114:117], v[58:61], v[2:17]
	v_exp_f32_e32 v94, v94
	v_exp_f32_e32 v95, v95
	v_exp_f32_e32 v96, v96
	v_exp_f32_e32 v97, v97

.Lf3_0_489:
	s_waitcnt lgkmcnt(14)
	v_mfma_f32_32x32x16_bf16 v[18:33], v[138:141], v[150:153], v[18:33]
	v_exp_f32_e32 v66, v66
	v_exp_f32_e32 v67, v67
	v_exp_f32_e32 v68, v68
	v_exp_f32_e32 v69, v69
	ds_read_b128 v[174:177], v202 offset:0
	ds_read_b128 v[170:173], v202 offset:512
	s_waitcnt lgkmcnt(14)
	v_mfma_f32_32x32x16_bf16 v[2:17], v[138:141], v[146:149], v[2:17]
	v_exp_f32_e32 v70, v70
	v_exp_f32_e32 v71, v71
	v_exp_f32_e32 v72, v72
	v_exp_f32_e32 v73, v73
	ds_read_b128 v[166:169], v202 offset:2048
	ds_read_b128 v[162:165], v202 offset:2560
	s_waitcnt lgkmcnt(14)
	v_mfma_f32_32x32x16_bf16 v[18:33], v[130:133], v[98:101], v[18:33]
	v_exp_f32_e32 v74, v74
	v_exp_f32_e32 v75, v75
	v_exp_f32_e32 v76, v76
	v_exp_f32_e32 v77, v77
	ds_read_b128 v[158:161], v202 offset:4096
	ds_read_b128 v[154:157], v202 offset:4608
	s_waitcnt lgkmcnt(14)
	v_mfma_f32_32x32x16_bf16 v[2:17], v[130:133], v[102:105], v[2:17]
	v_exp_f32_e32 v78, v78
	v_exp_f32_e32 v79, v79
	v_exp_f32_e32 v80, v80
	v_exp_f32_e32 v81, v81
	ds_read_b128 v[150:153], v202 offset:6144
	ds_read_b128 v[146:149], v202 offset:6656
	s_waitcnt lgkmcnt(14)
	v_mfma_f32_32x32x16_bf16 v[18:33], v[122:125], v[106:109], v[18:33]
	v_exp_f32_e32 v50, v50
	v_exp_f32_e32 v51, v51
	v_exp_f32_e32 v52, v52
	v_exp_f32_e32 v53, v53
	s_waitcnt lgkmcnt(12)
	v_mfma_f32_32x32x16_bf16 v[2:17], v[122:125], v[82:85], v[2:17]
	v_exp_f32_e32 v54, v54
	v_exp_f32_e32 v55, v55
	v_exp_f32_e32 v56, v56
	v_exp_f32_e32 v57, v57
	s_waitcnt lgkmcnt(10)
	v_mfma_f32_32x32x16_bf16 v[18:33], v[114:117], v[86:89], v[18:33]
	v_exp_f32_e32 v58, v58
	v_exp_f32_e32 v59, v59
	v_exp_f32_e32 v60, v60
	v_exp_f32_e32 v61, v61
	s_waitcnt vmcnt(2) lgkmcnt(0)
	s_barrier
	s_waitcnt lgkmcnt(8)
	v_mfma_f32_32x32x16_bf16 v[2:17], v[114:117], v[90:93], v[2:17]
	v_exp_f32_e32 v62, v62
	v_exp_f32_e32 v63, v63
	v_exp_f32_e32 v64, v64
	v_exp_f32_e32 v65, v65

.Lf3_1_486:
	s_waitcnt lgkmcnt(14)
	v_mfma_f32_32x32x16_bf16 v[18:33], v[138:141], v[178:181], v[18:33]
	v_exp_f32_e32 v98, v98
	v_exp_f32_e32 v99, v99
	v_exp_f32_e32 v100, v100
	v_exp_f32_e32 v101, v101
	ds_read_b128 v[62:65], v202 offset:8192
	ds_read_b128 v[178:181], v202 offset:10240
	s_waitcnt lgkmcnt(14)
	v_mfma_f32_32x32x16_bf16 v[2:17], v[138:141], v[174:177], v[2:17]
	v_exp_f32_e32 v102, v102
	v_exp_f32_e32 v103, v103
	v_exp_f32_e32 v104, v104
	v_exp_f32_e32 v105, v105
	ds_read_b128 v[174:177], v202 offset:8704
	ds_read_b128 v[170:173], v202 offset:10752
	s_waitcnt lgkmcnt(14)
	v_mfma_f32_32x32x16_bf16 v[18:33], v[130:133], v[66:69], v[18:33]
	v_exp_f32_e32 v106, v106
	v_exp_f32_e32 v107, v107
	v_exp_f32_e32 v108, v108
	v_exp_f32_e32 v109, v109
	ds_read_b128 v[166:169], v202 offset:12288
	ds_read_b128 v[162:165], v202 offset:12800
	s_waitcnt lgkmcnt(14)
	v_mfma_f32_32x32x16_bf16 v[2:17], v[130:133], v[70:73], v[2:17]
	v_exp_f32_e32 v110, v110
	v_exp_f32_e32 v111, v111
	v_exp_f32_e32 v112, v112
	v_exp_f32_e32 v113, v113
	ds_read_b128 v[158:161], v202 offset:14336
	ds_read_b128 v[154:157], v202 offset:14848
	s_waitcnt lgkmcnt(14)
	v_mfma_f32_32x32x16_bf16 v[18:33], v[122:125], v[74:77], v[18:33]
	v_exp_f32_e32 v82, v82
	v_exp_f32_e32 v83, v83
	v_exp_f32_e32 v84, v84
	v_exp_f32_e32 v85, v85
	s_waitcnt lgkmcnt(12)
	v_mfma_f32_32x32x16_bf16 v[2:17], v[122:125], v[50:53], v[2:17]
	v_exp_f32_e32 v86, v86
	v_exp_f32_e32 v87, v87
	v_exp_f32_e32 v88, v88
	v_exp_f32_e32 v89, v89
	s_waitcnt lgkmcnt(10)
	v_mfma_f32_32x32x16_bf16 v[18:33], v[114:117], v[54:57], v[18:33]
	v_exp_f32_e32 v90, v90
	v_exp_f32_e32 v91, v91
	v_exp_f32_e32 v92, v92
	v_exp_f32_e32 v93, v93
	s_waitcnt vmcnt(2) lgkmcnt(0)
	s_barrier
	s_waitcnt lgkmcnt(8)
	v_mfma_f32_32x32x16_bf16 v[2:17], v[114:117], v[58:61], v[2:17]
	v_exp_f32_e32 v94, v94
	v_exp_f32_e32 v95, v95
	v_exp_f32_e32 v96, v96
	v_exp_f32_e32 v97, v97

.Lf3_1_489:
	s_waitcnt lgkmcnt(14)
	v_mfma_f32_32x32x16_bf16 v[18:33], v[138:141], v[150:153], v[18:33]
	v_exp_f32_e32 v66, v66
	v_exp_f32_e32 v67, v67
	v_exp_f32_e32 v68, v68
	v_exp_f32_e32 v69, v69
	ds_read_b128 v[174:177], v202 offset:16384
	ds_read_b128 v[170:173], v202 offset:16896
	s_waitcnt lgkmcnt(14)
	v_mfma_f32_32x32x16_bf16 v[2:17], v[138:141], v[146:149], v[2:17]
	v_exp_f32_e32 v70, v70
	v_exp_f32_e32 v71, v71
	v_exp_f32_e32 v72, v72
	v_exp_f32_e32 v73, v73
	ds_read_b128 v[166:169], v202 offset:18432
	ds_read_b128 v[162:165], v202 offset:18944
	s_waitcnt lgkmcnt(14)
	v_mfma_f32_32x32x16_bf16 v[18:33], v[130:133], v[98:101], v[18:33]
	v_exp_f32_e32 v74, v74
	v_exp_f32_e32 v75, v75
	v_exp_f32_e32 v76, v76
	v_exp_f32_e32 v77, v77
	ds_read_b128 v[158:161], v202 offset:20480
	ds_read_b128 v[154:157], v202 offset:20992
	s_waitcnt lgkmcnt(14)
	v_mfma_f32_32x32x16_bf16 v[2:17], v[130:133], v[102:105], v[2:17]
	v_exp_f32_e32 v78, v78
	v_exp_f32_e32 v79, v79
	v_exp_f32_e32 v80, v80
	v_exp_f32_e32 v81, v81
	ds_read_b128 v[150:153], v202 offset:22528
	ds_read_b128 v[146:149], v202 offset:23040
	s_waitcnt lgkmcnt(14)
	v_mfma_f32_32x32x16_bf16 v[18:33], v[122:125], v[106:109], v[18:33]
	v_exp_f32_e32 v50, v50
	v_exp_f32_e32 v51, v51
	v_exp_f32_e32 v52, v52
	v_exp_f32_e32 v53, v53
	s_waitcnt lgkmcnt(12)
	v_mfma_f32_32x32x16_bf16 v[2:17], v[122:125], v[82:85], v[2:17]
	v_exp_f32_e32 v54, v54
	v_exp_f32_e32 v55, v55
	v_exp_f32_e32 v56, v56
	v_exp_f32_e32 v57, v57
	s_waitcnt lgkmcnt(10)
	v_mfma_f32_32x32x16_bf16 v[18:33], v[114:117], v[86:89], v[18:33]
	v_exp_f32_e32 v58, v58
	v_exp_f32_e32 v59, v59
	v_exp_f32_e32 v60, v60
	v_exp_f32_e32 v61, v61
	s_waitcnt vmcnt(2) lgkmcnt(0)
	s_barrier
	s_waitcnt lgkmcnt(8)
	v_mfma_f32_32x32x16_bf16 v[2:17], v[114:117], v[90:93], v[2:17]
	v_exp_f32_e32 v62, v62
	v_exp_f32_e32 v63, v63
	v_exp_f32_e32 v64, v64
	v_exp_f32_e32 v65, v65

.Lf3_2_486:
	s_waitcnt lgkmcnt(14)
	v_mfma_f32_32x32x16_bf16 v[18:33], v[138:141], v[178:181], v[18:33]
	v_exp_f32_e32 v98, v98
	v_exp_f32_e32 v99, v99
	v_exp_f32_e32 v100, v100
	v_exp_f32_e32 v101, v101
	ds_read_b128 v[62:65], v202 offset:0
	ds_read_b128 v[178:181], v202 offset:2048
	s_waitcnt lgkmcnt(14)
	v_mfma_f32_32x32x16_bf16 v[2:17], v[138:141], v[174:177], v[2:17]
	v_exp_f32_e32 v102, v102
	v_exp_f32_e32 v103, v103
	v_exp_f32_e32 v104, v104
	v_exp_f32_e32 v105, v105
	ds_read_b128 v[174:177], v202 offset:512
	ds_read_b128 v[170:173], v202 offset:2560
	s_waitcnt lgkmcnt(14)
	v_mfma_f32_32x32x16_bf16 v[18:33], v[130:133], v[66:69], v[18:33]
	v_exp_f32_e32 v106, v106
	v_exp_f32_e32 v107, v107
	v_exp_f32_e32 v108, v108
	v_exp_f32_e32 v109, v109
	ds_read_b128 v[166:169], v202 offset:4096
	ds_read_b128 v[162:165], v202 offset:4608
	s_waitcnt lgkmcnt(14)
	v_mfma_f32_32x32x16_bf16 v[2:17], v[130:133], v[70:73], v[2:17]
	v_exp_f32_e32 v110, v110
	v_exp_f32_e32 v111, v111
	v_exp_f32_e32 v112, v112
	v_exp_f32_e32 v113, v113
	ds_read_b128 v[158:161], v202 offset:6144
	ds_read_b128 v[154:157], v202 offset:6656
	s_waitcnt lgkmcnt(14)
	v_mfma_f32_32x32x16_bf16 v[18:33], v[122:125], v[74:77], v[18:33]
	v_exp_f32_e32 v82, v82
	v_exp_f32_e32 v83, v83
	v_exp_f32_e32 v84, v84
	v_exp_f32_e32 v85, v85
	s_waitcnt lgkmcnt(12)
	v_mfma_f32_32x32x16_bf16 v[2:17], v[122:125], v[50:53], v[2:17]
	v_exp_f32_e32 v86, v86
	v_exp_f32_e32 v87, v87
	v_exp_f32_e32 v88, v88
	v_exp_f32_e32 v89, v89
	s_waitcnt lgkmcnt(10)
	v_mfma_f32_32x32x16_bf16 v[18:33], v[114:117], v[54:57], v[18:33]
	v_exp_f32_e32 v90, v90
	v_exp_f32_e32 v91, v91
	v_exp_f32_e32 v92, v92
	v_exp_f32_e32 v93, v93
	s_waitcnt vmcnt(2) lgkmcnt(0)
	s_barrier
	s_waitcnt lgkmcnt(8)
	v_mfma_f32_32x32x16_bf16 v[2:17], v[114:117], v[58:61], v[2:17]
	v_exp_f32_e32 v94, v94
	v_exp_f32_e32 v95, v95
	v_exp_f32_e32 v96, v96
	v_exp_f32_e32 v97, v97

.Lf3_2_489:
	s_waitcnt lgkmcnt(14)
	v_mfma_f32_32x32x16_bf16 v[18:33], v[138:141], v[150:153], v[18:33]
	v_exp_f32_e32 v66, v66
	v_exp_f32_e32 v67, v67
	v_exp_f32_e32 v68, v68
	v_exp_f32_e32 v69, v69
	ds_read_b128 v[174:177], v202 offset:8192
	ds_read_b128 v[170:173], v202 offset:8704
	s_waitcnt lgkmcnt(14)
	v_mfma_f32_32x32x16_bf16 v[2:17], v[138:141], v[146:149], v[2:17]
	v_exp_f32_e32 v70, v70
	v_exp_f32_e32 v71, v71
	v_exp_f32_e32 v72, v72
	v_exp_f32_e32 v73, v73
	ds_read_b128 v[166:169], v202 offset:10240
	ds_read_b128 v[162:165], v202 offset:10752
	s_waitcnt lgkmcnt(14)
	v_mfma_f32_32x32x16_bf16 v[18:33], v[130:133], v[98:101], v[18:33]
	v_exp_f32_e32 v74, v74
	v_exp_f32_e32 v75, v75
	v_exp_f32_e32 v76, v76
	v_exp_f32_e32 v77, v77
	ds_read_b128 v[158:161], v202 offset:12288
	ds_read_b128 v[154:157], v202 offset:12800
	s_waitcnt lgkmcnt(14)
	v_mfma_f32_32x32x16_bf16 v[2:17], v[130:133], v[102:105], v[2:17]
	v_exp_f32_e32 v78, v78
	v_exp_f32_e32 v79, v79
	v_exp_f32_e32 v80, v80
	v_exp_f32_e32 v81, v81
	ds_read_b128 v[150:153], v202 offset:14336
	ds_read_b128 v[146:149], v202 offset:14848
	s_waitcnt lgkmcnt(14)
	v_mfma_f32_32x32x16_bf16 v[18:33], v[122:125], v[106:109], v[18:33]
	v_exp_f32_e32 v50, v50
	v_exp_f32_e32 v51, v51
	v_exp_f32_e32 v52, v52
	v_exp_f32_e32 v53, v53
	s_waitcnt lgkmcnt(12)
	v_mfma_f32_32x32x16_bf16 v[2:17], v[122:125], v[82:85], v[2:17]
	v_exp_f32_e32 v54, v54
	v_exp_f32_e32 v55, v55
	v_exp_f32_e32 v56, v56
	v_exp_f32_e32 v57, v57
	s_waitcnt lgkmcnt(10)
	v_mfma_f32_32x32x16_bf16 v[18:33], v[114:117], v[86:89], v[18:33]
	v_exp_f32_e32 v58, v58
	v_exp_f32_e32 v59, v59
	v_exp_f32_e32 v60, v60
	v_exp_f32_e32 v61, v61
	s_waitcnt vmcnt(2) lgkmcnt(0)
	s_barrier
	s_waitcnt lgkmcnt(8)
	v_mfma_f32_32x32x16_bf16 v[2:17], v[114:117], v[90:93], v[2:17]
	v_exp_f32_e32 v62, v62
	v_exp_f32_e32 v63, v63
	v_exp_f32_e32 v64, v64
	v_exp_f32_e32 v65, v65
